# weight conversions moved off the critical path into idle last-round workgroups of the multi-round GEMM phases (same converter code, swapped first/stride)
# speedup vs baseline: 1.0090x; 1.0090x over previous
.LBB0_76:
	s_mov_b32 s98, 0
	s_mov_b32 s17, 7
	s_cmp_eq_u32 s88, 0
	s_cbranch_scc1 .LBB0_81
	s_cmp_eq_u32 s88, 1
	s_cselect_b32 s17, 0x38, 0
	s_cselect_b32 s99, 0x96, 0
	s_cmp_eq_u32 s88, 3
	s_cselect_b32 s17, 0xc0, s17
	s_cselect_b32 s99, 0x8e, s99
	s_cmp_eq_u32 s88, 10
	s_cselect_b32 s17, 0x100, s17
	s_cselect_b32 s99, 0x96, s99
	s_cmp_eq_u32 s88, 12
	s_cselect_b32 s17, 0xe00, s17
	s_cselect_b32 s99, 0x96, s99
	s_cmp_eq_u32 s17, 0
	s_cbranch_scc1 .LBB0_78
	s_cmp_lt_u32 s2, s99
	s_cbranch_scc0 .Lcv_idle
.LBB0_78:
	s_mov_b32 s98, 0
	s_branch .LBB0_268
.Lcv_idle:
	v_writelane_b32 v100, s2, 0
	v_writelane_b32 v100, s3, 1
	v_writelane_b32 v100, s90, 2
	v_writelane_b32 v100, s33, 3
	v_writelane_b32 v100, s18, 4
	v_writelane_b32 v100, s91, 5
	v_writelane_b32 v100, s68, 6
	v_writelane_b32 v100, s94, 7
	v_writelane_b32 v100, s95, 8
	v_writelane_b32 v100, s76, 9
	v_writelane_b32 v100, s96, 10
	v_writelane_b32 v100, s71, 11
	v_readlane_b32 s100, v254, 19
	s_nop 3
	v_writelane_b32 v100, s100, 12
	v_readlane_b32 s100, v254, 20
	s_nop 3
	v_writelane_b32 v100, s100, 13
	v_readlane_b32 s100, v254, 21
	s_nop 3
	v_writelane_b32 v100, s100, 14
	v_readlane_b32 s100, v254, 22
	s_nop 3
	v_writelane_b32 v100, s100, 15
	v_readlane_b32 s100, v254, 23
	s_nop 3
	v_writelane_b32 v100, s100, 16
	v_readlane_b32 s100, v254, 24
	s_nop 3
	v_writelane_b32 v100, s100, 17
	v_readlane_b32 s100, v254, 25
	s_nop 3
	v_writelane_b32 v100, s100, 18
	s_sub_u32 s2, s2, s99
	s_sub_u32 s90, 0x100, s99
	s_mov_b32 s3, 0
	s_lshl_b32 s33, s90, 1
	s_lshl_b32 s18, s90, 2
	s_mul_i32 s91, s90, 3
	s_mul_i32 s68, s90, 5
	s_mul_i32 s94, s90, 6
	s_mul_i32 s95, s90, 7
	s_add_i32 s76, s90, s2
	s_add_i32 s96, s76, s90
	s_add_i32 s71, s96, s90
	s_mov_b32 s100, 0
	s_nop 3
	v_writelane_b32 v254, s2, 19
	v_writelane_b32 v254, s100, 20
	v_writelane_b32 v254, s76, 21
	v_writelane_b32 v254, s100, 22
	v_writelane_b32 v254, s96, 23
	v_writelane_b32 v254, s100, 24
	v_writelane_b32 v254, s71, 25
	s_mov_b32 s98, 1

.LBB0_268:
	s_cmp_eq_u32 s98, 0
	s_cbranch_scc1 .Lcv_keep
	v_readlane_b32 s100, v100, 12
	s_nop 3
	v_writelane_b32 v254, s100, 19
	v_readlane_b32 s100, v100, 13
	s_nop 3
	v_writelane_b32 v254, s100, 20
	v_readlane_b32 s100, v100, 14
	s_nop 3
	v_writelane_b32 v254, s100, 21
	v_readlane_b32 s100, v100, 15
	s_nop 3
	v_writelane_b32 v254, s100, 22
	v_readlane_b32 s100, v100, 16
	s_nop 3
	v_writelane_b32 v254, s100, 23
	v_readlane_b32 s100, v100, 17
	s_nop 3
	v_writelane_b32 v254, s100, 24
	v_readlane_b32 s100, v100, 18
	s_nop 3
	v_writelane_b32 v254, s100, 25
	v_readlane_b32 s2, v100, 0
	v_readlane_b32 s3, v100, 1
	v_readlane_b32 s90, v100, 2
	v_readlane_b32 s33, v100, 3
	v_readlane_b32 s18, v100, 4
	v_readlane_b32 s91, v100, 5
	v_readlane_b32 s68, v100, 6
	v_readlane_b32 s94, v100, 7
	v_readlane_b32 s95, v100, 8
	v_readlane_b32 s76, v100, 9
	v_readlane_b32 s96, v100, 10
	v_readlane_b32 s71, v100, 11
	s_mov_b32 s98, 0
	s_nop 3

.LBB0_606:
	s_and_b64 vcc, exec, s[0:1]
	s_cbranch_vccz .LBB0_508
	s_waitcnt vmcnt(0)
	v_lshrrev_b32_e32 v90, 4, v241
	v_bfe_u32 v91, v241, 3, 1
	v_and_b32_e32 v86, 15, v241
	v_lshlrev_b32_e32 v90, 1, v90
	v_lshlrev_b32_e32 v86, 4, v86
	v_add_u32_e32 v92, v90, v91
	v_xor_b32_e32 v91, 1, v91
	v_add_u32_e32 v93, v90, v91
	s_lshl_b32 s0, s10, 5
	v_lshlrev_b32_e32 v89, 2, v92
	v_add_u32_e32 v92, s0, v92
	v_add_u32_e32 v93, s0, v93
	v_add_u32_e32 v89, 0x18000, v89
	v_lshlrev_b32_e32 v87, 2, v92
	v_lshlrev_b32_e32 v88, 2, v93
	v_mov_b32_e32 v0, 0
	v_mov_b32_e32 v1, 0
	v_mov_b32_e32 v2, 0
	v_mov_b32_e32 v3, 0
	v_mov_b32_e32 v4, 0
	v_mov_b32_e32 v5, 0
	v_mov_b32_e32 v6, 0
	v_mov_b32_e32 v7, 0
	s_waitcnt lgkmcnt(0)
	s_barrier
	s_mov_b32 s4, 0
	s_nop 0
	s_nop 0
	s_nop 0
	s_nop 0
	s_nop 0
	s_nop 0
	s_nop 0
	s_nop 0
	s_nop 0
	s_nop 0
	s_nop 0

	.amdhsa_kernel _Z10hybrid_fwd4Args
		.amdhsa_group_segment_fixed_size 0
		.amdhsa_private_segment_fixed_size 0
		.amdhsa_kernarg_size 504
		.amdhsa_user_sgpr_count 2
		.amdhsa_user_sgpr_dispatch_ptr 0
		.amdhsa_user_sgpr_queue_ptr 0
		.amdhsa_user_sgpr_kernarg_segment_ptr 1
		.amdhsa_user_sgpr_dispatch_id 0
		.amdhsa_user_sgpr_kernarg_preload_length 0
		.amdhsa_user_sgpr_kernarg_preload_offset 0
		.amdhsa_user_sgpr_private_segment_size 0
		.amdhsa_uses_dynamic_stack 0
		.amdhsa_enable_private_segment 0
		.amdhsa_system_sgpr_workgroup_id_x 1
		.amdhsa_system_sgpr_workgroup_id_y 0
		.amdhsa_system_sgpr_workgroup_id_z 0
		.amdhsa_system_sgpr_workgroup_info 0
		.amdhsa_system_vgpr_workitem_id 2
		.amdhsa_next_free_vgpr 256
		.amdhsa_next_free_sgpr 101
		.amdhsa_accum_offset 256
		.amdhsa_reserve_vcc 1
		.amdhsa_float_round_mode_32 0
		.amdhsa_float_round_mode_16_64 0
		.amdhsa_float_denorm_mode_32 3
		.amdhsa_float_denorm_mode_16_64 3
		.amdhsa_dx10_clamp 1
		.amdhsa_ieee_mode 1
		.amdhsa_fp16_overflow 0
		.amdhsa_tg_split 0
		.amdhsa_exception_fp_ieee_invalid_op 0
		.amdhsa_exception_fp_denorm_src 0
		.amdhsa_exception_fp_ieee_div_zero 0
		.amdhsa_exception_fp_ieee_overflow 0
		.amdhsa_exception_fp_ieee_underflow 0
		.amdhsa_exception_fp_ieee_inexact 0
		.amdhsa_exception_int_div_zero 0
	.end_amdhsa_kernel

amdhsa.kernels:
  - .agpr_count:     0
    .args:
      - .offset:         0
        .size:           248
        .value_kind:     by_value
      - .offset:         248
        .size:           4
        .value_kind:     hidden_block_count_x
      - .offset:         252
        .size:           4
        .value_kind:     hidden_block_count_y
      - .offset:         256
        .size:           4
        .value_kind:     hidden_block_count_z
      - .offset:         260
        .size:           2
        .value_kind:     hidden_group_size_x
      - .offset:         262
        .size:           2
        .value_kind:     hidden_group_size_y
      - .offset:         264
        .size:           2
        .value_kind:     hidden_group_size_z
      - .offset:         266
        .size:           2
        .value_kind:     hidden_remainder_x
      - .offset:         268
        .size:           2
        .value_kind:     hidden_remainder_y
      - .offset:         270
        .size:           2
        .value_kind:     hidden_remainder_z
      - .offset:         288
        .size:           8
        .value_kind:     hidden_global_offset_x
      - .offset:         296
        .size:           8
        .value_kind:     hidden_global_offset_y
      - .offset:         304
        .size:           8
        .value_kind:     hidden_global_offset_z
      - .offset:         312
        .size:           2
        .value_kind:     hidden_grid_dims
      - .offset:         336
        .size:           8
        .value_kind:     hidden_multigrid_sync_arg
      - .offset:         368
        .size:           4
        .value_kind:     hidden_dynamic_lds_size
    .group_segment_fixed_size: 0
    .kernarg_segment_align: 8
    .kernarg_segment_size: 504
    .language:       OpenCL C
    .language_version:
      - 2
      - 0
    .max_flat_workgroup_size: 512
    .name:           _Z10hybrid_fwd4Args
    .private_segment_fixed_size: 0
    .sgpr_count:     107
    .sgpr_spill_count: 255
    .symbol:         _Z10hybrid_fwd4Args.kd
    .uniform_work_group_size: 1
    .uses_dynamic_stack: false
    .vgpr_count:     256
    .vgpr_spill_count: 0
    .wavefront_size: 64
